# bundle: v42 + row prefetch in layer-1 rmsnorm + relaxed chain waits + peeled first K iteration + batched combine_merge loads (run 1)
# speedup vs baseline: 1.0114x; 1.0114x over previous
; #define GAS __attribute__((address_space(1)))
; __device__ __forceinline__ float bf_lo(unsigned u) { return __uint_as_float(u << 16); }
; __device__ __forceinline__ float bf_hi(unsigned u) { return __uint_as_float(u & 0xffff0000u); }
;     __device__ __forceinline__ GAS unsigned char* wsp() const { return (GAS unsigned char*)rd(18); }
; #define F_norm_g F.in(7)
; __device__ __forceinline__ void phase_xn_fused(Frame& F, int l) {
;     ...
;     const int gw = F.vcu * 8 + F.wave, NGW = F.G * 8;
;     GAS bf16* HB = (GAS bf16*)(F.wsp() + WS_H); GAS bf16* XN = (GAS bf16*)(F.wsp() + WS_XN); const GAS bf16* sl = (const GAS bf16*)(F.wsp() + WS_SLAB_O); const GAS float* gn = F_norm_g + (size_t)l * D;
;     for (int r = gw; r < MTOT; r += NGW) {
;         if (r >= MP && r < MPAD) { zero_xn_row(XN + (size_t)r * D, lane); continue; }
;         GAS v2u* xb = (GAS v2u*)(HB + (size_t)r * D) + lane; const int pm = r >> 8, rr = r & 255;
;         f32x4 v[4]; float s = 0.f;
; #pragma unroll
;         for (int j = 0; j < 4; ++j) { const int idx = tab[4 * pm + j]; const v2u t = xb[64 * j]; v[j] = (f32x4){bf_lo(t.x), bf_hi(t.x), bf_lo(t.y), bf_hi(t.y)};
.LBB0_109:
	s_or_b64 exec, exec, s[26:27]
	v_readlane_b32 s12, v241, 45
	v_mov_b32_e32 v0, s18
	s_waitcnt lgkmcnt(0)
	v_mov_b32_e32 v3, s12
	s_barrier
	ds_read_b64 v[0:1], v0
	s_waitcnt vmcnt(0)
	ds_read_b64 v[4:5], v3
	v_readlane_b32 s14, v243, 5
	v_readlane_b32 s15, v243, 6
	s_andn2_b64 vcc, exec, s[14:15]
	s_waitcnt lgkmcnt(1)
	v_readfirstlane_b32 s27, v1
	v_readfirstlane_b32 s26, v0
	s_waitcnt lgkmcnt(0)
	v_readfirstlane_b32 s12, v5
	v_readfirstlane_b32 s13, v4
	s_cbranch_vccnz .LBB0_124
	v_mbcnt_lo_u32_b32 v0, -1, v2
	v_mbcnt_hi_u32_b32 v4, -1, v0
	v_lshlrev_b32_e32 v0, 2, v4
	v_ashrrev_i32_e32 v5, 31, v4
	v_ashrrev_i32_e32 v1, 31, v0
	v_mov_b32_e32 v6, s13
	v_mov_b32_e32 v7, s12
	v_lshl_add_u64 v[0:1], v[0:1], 1, s[26:27]
	s_mov_b64 s[12:13], 0xfd80000
	v_lshlrev_b64 v[8:9], 3, v[4:5]
	v_lshl_add_u64 v[0:1], v[0:1], 0, s[12:13]
	v_lshl_add_u64 v[2:3], s[26:27], 0, v[8:9]
	s_mov_b64 s[12:13], 0x9000000
	v_lshl_add_u64 v[2:3], v[2:3], 0, s[12:13]
	v_lshl_add_u64 v[4:5], v[4:5], 4, v[6:7]
	s_mov_b64 s[12:13], 0x1000
	v_lshl_add_u64 v[4:5], v[4:5], 0, s[12:13]
	v_readlane_b32 s12, v241, 30
	s_add_u32 s12, s26, s12
	v_readlane_b32 s13, v241, 31
	s_addc_u32 s13, s27, s13
	v_readlane_b32 s26, v241, 24
	v_readlane_b32 s14, v241, 28
	v_lshl_add_u64 v[6:7], s[12:13], 0, v[8:9]
	v_readlane_b32 s27, v241, 25
	v_readlane_b32 s12, v241, 19
	s_mov_b32 s13, s14
	v_readlane_b32 s15, v241, 29
	v_add_co_u32_e32 v42, vcc, 0xfb700000, v6
	v_readlane_b32 s98, v241, 57
	v_addc_co_u32_e32 v43, vcc, -1, v7, vcc
	v_readlane_b32 s99, v241, 58
	global_load_dwordx2 v[44:45], v[42:43], off offset:-1024
	global_load_dwordx2 v[46:47], v[42:43], off offset:-512
	global_load_dwordx2 v[48:49], v[42:43], off
	global_load_dwordx2 v[50:51], v[42:43], off offset:512
	global_load_dwordx4 v[52:55], v[4:5], off
	global_load_dwordx4 v[56:59], v[4:5], off offset:1024
	global_load_dwordx4 v[60:63], v[4:5], off offset:2048
	global_load_dwordx4 v[64:67], v[4:5], off offset:3072
	s_waitcnt vmcnt(0)
	s_branch .Lxn_top2

; #define GAS __attribute__((address_space(1)))
; __device__ __forceinline__ unsigned cvt_pk_bf16(float lo, float hi) { const f32x2 v = {lo, hi}; return __builtin_bit_cast(unsigned, __builtin_convertvector(v, bf16n2)); }
; __device__ __forceinline__ float bf_lo(unsigned u) { return __uint_as_float(u << 16); }
; __device__ __forceinline__ float bf_hi(unsigned u) { return __uint_as_float(u & 0xffff0000u); }
; __device__ __forceinline__ void phase_xn_fused(Frame& F, int l) {
;     ...
;     for (int r = gw; r < MTOT; r += NGW) {
;         if (r >= MP && r < MPAD) { zero_xn_row(XN + (size_t)r * D, lane); continue; }
;         GAS v2u* xb = (GAS v2u*)(HB + (size_t)r * D) + lane; const int pm = r >> 8, rr = r & 255;
;         f32x4 v[4]; float s = 0.f;
; #pragma unroll
;         for (int j = 0; j < 4; ++j) { const int idx = tab[4 * pm + j]; const v2u t = xb[64 * j]; v[j] = (f32x4){bf_lo(t.x), bf_hi(t.x), bf_lo(t.y), bf_hi(t.y)};
;             if (idx >= 0) { v[j] += slab4_sum(sl + (size_t)(4 * idx) * 65536 + (size_t)rr * 256 + 4 * lane); v2u o; o.x = cvt_pk_bf16(v[j][0], v[j][1]); o.y = cvt_pk_bf16(v[j][2], v[j][3]); xb[64 * j] = o; }
.LBB0_112:
	s_waitcnt vmcnt(4)
.Lxn_top2:
	v_mov_b64_e32 v[80:81], v[44:45]
	v_mov_b64_e32 v[82:83], v[46:47]
	v_mov_b64_e32 v[84:85], v[48:49]
	v_mov_b64_e32 v[86:87], v[50:51]
	v_lshl_add_u64 v[42:43], v[42:43], 0, s[98:99]
	global_load_dwordx2 v[44:45], v[42:43], off offset:-1024
	global_load_dwordx2 v[46:47], v[42:43], off offset:-512
	global_load_dwordx2 v[48:49], v[42:43], off
	global_load_dwordx2 v[50:51], v[42:43], off offset:512
	s_and_b32 s14, s13, 0xffffff80
	s_cmpk_lg_i32 s14, 0x4080
	s_mov_b64 s[34:35], -1
	s_cbranch_scc0 .LBB0_122
	s_ashr_i32 s14, s13, 6
	s_lshl_b32 s14, s14, 2
	s_and_b32 s14, s14, -16
	s_add_i32 s14, s14, 0
	v_mov_b32_e32 v10, s14
	ds_read_b32 v12, v10
	s_and_b32 s15, s12, 0xff00
	s_lshl_b32 s20, s15, 1
	v_lshl_add_u64 v[20:21], v[0:1], 0, s[20:21]
	s_waitcnt lgkmcnt(0)
	v_cmp_gt_i32_e32 vcc, 0, v12
	s_and_b64 vcc, exec, vcc
	v_lshlrev_b32_e32 v10, 16, v80
	v_and_b32_e32 v11, 0xffff0000, v80
	v_lshlrev_b32_e32 v8, 16, v81
	v_and_b32_e32 v9, 0xffff0000, v81
	s_cbranch_vccnz .LBB0_115
	v_lshlrev_b32_e32 v172, 2, v12
	v_lshlrev_b64 v[12:13], 17, v[172:173]
	v_lshl_add_u64 v[12:13], v[20:21], 0, v[12:13]
	v_add_co_u32_e32 v16, vcc, 0x20000, v12
	global_load_dwordx2 v[14:15], v[12:13], off
	s_nop 0
	v_addc_co_u32_e32 v17, vcc, 0, v13, vcc
	v_add_co_u32_e32 v18, vcc, 0x40000, v12
	global_load_dwordx2 v[16:17], v[16:17], off
	s_nop 0
	v_addc_co_u32_e32 v19, vcc, 0, v13, vcc
	v_add_co_u32_e32 v12, vcc, 0x60000, v12
	global_load_dwordx2 v[18:19], v[18:19], off
	s_nop 0
	v_addc_co_u32_e32 v13, vcc, 0, v13, vcc
	global_load_dwordx2 v[12:13], v[12:13], off
	s_mov_b32 s16, 0xfb6ffc00
	s_mov_b32 s17, -1
	v_lshl_add_u64 v[22:23], v[6:7], 0, s[16:17]
	s_waitcnt vmcnt(3)
	v_lshlrev_b32_e32 v24, 16, v14
	v_and_b32_e32 v25, 0xffff0000, v14
	v_lshlrev_b32_e32 v14, 16, v15
	v_and_b32_e32 v15, 0xffff0000, v15
	s_waitcnt vmcnt(2)
	v_lshlrev_b32_e32 v26, 16, v16
	v_and_b32_e32 v27, 0xffff0000, v16
	v_lshlrev_b32_e32 v16, 16, v17
	v_and_b32_e32 v17, 0xffff0000, v17
	v_pk_add_f32 v[14:15], v[14:15], v[16:17]
	v_pk_add_f32 v[16:17], v[24:25], v[26:27]
	s_waitcnt vmcnt(1)
	v_lshlrev_b32_e32 v24, 16, v18
	v_and_b32_e32 v25, 0xffff0000, v18
	v_lshlrev_b32_e32 v18, 16, v19
	v_and_b32_e32 v19, 0xffff0000, v19
	s_waitcnt vmcnt(0)
	v_lshlrev_b32_e32 v26, 16, v12
	v_and_b32_e32 v27, 0xffff0000, v12
	v_lshlrev_b32_e32 v12, 16, v13
	v_and_b32_e32 v13, 0xffff0000, v13
	v_pk_add_f32 v[12:13], v[18:19], v[12:13]
	v_pk_add_f32 v[18:19], v[24:25], v[26:27]
	v_pk_add_f32 v[12:13], v[14:15], v[12:13]
	v_pk_add_f32 v[16:17], v[16:17], v[18:19]
	v_pk_add_f32 v[8:9], v[8:9], v[12:13]
	v_pk_add_f32 v[10:11], v[10:11], v[16:17]
	v_cvt_pk_bf16_f32 v13, v8, v9
	v_cvt_pk_bf16_f32 v12, v10, v11
	global_store_dwordx2 v[22:23], v[12:13], off
